# kernarg pointer reloads at phase starts: adjacent s_load_dwordx2 blocks issued together with one lgkmcnt(0) wait per run instead of one per load (40 waits removed)
# speedup vs baseline: 1.0013x; 1.0013x over previous
; #define LAS __attribute__((address_space(3)))
; #define PH(n) if (ONLY < 0 || ONLY == (n))
; #define KARG(i) ({ unsigned long long p_; asm volatile("s_load_dwordx2 %0, %1, %2\n\ts_waitcnt lgkmcnt(0)" : "=s"(p_) : "s"((unsigned long long)__builtin_amdgcn_kernarg_segment_ptr()), "n"((i) * 8)); p_; })
; #define IN(i) ((const float*)KARG(i))
; #define WSB(off) ((bf16*)((unsigned char*)KARG(20) + (off)))
; #define WSF(off) ((float*)((unsigned char*)KARG(20) + (off)))
; __global__ void __launch_bounds__(NWAVES * 64, 2) mk_fwd(Args args) {
;     ...
;     PH(0) { PHASE_VARS
;         if (CGFIRST && bx == 0) { unsigned* bw = (unsigned*)((unsigned char*)KARG(20) + WS_BAR); for (int i = tid; i < 16384; i += NWAVES * 64) __hip_atomic_store(bw + i, 0u, __ATOMIC_RELAXED, __HIP_MEMORY_SCOPE_AGENT); }
;         const float* x = IN(0); const float* mem = IN(1); const float* g_mix = IN(2); const float* w_in = IN(3); const float* b_f = IN(4); const float* g_mem = IN(11);
;         bf16* XN = WSB(WS_XN); bf16* MEMN = WSB(WS_MEMN); float* LOGF = WSF(WS_LOGF);
;         LAS float* scr = (LAS float*)(lds + wave * 16640);
;         constexpr int I_IN = 16 * 40, I_MKV = 16 * 32;
;         for (int it = gw; it < I_IN + I_MKV; it += NGW) {
;             int r = it;
;             if (r < I_IN) { const int kb = r / 40, nb = r % 40; const int sc = 64 * nb; int dr = sc;
;                 if (sc < 1024) { const int i0 = sc < 512 ? sc : sc - 512; dr = 256 * (i0 / 128) + (i0 % 128) + (sc < 512 ? 0 : 128); }
;                 transpose_item(w_in, DIN, 1024, nullptr, WSB(WS_WIN), kb, sc, dr, scr, lane); continue; } r -= I_IN;
;             { const int kb = r / 32, nb = r % 32; transpose_item(IN(13), 2048, 1024, nullptr, WSB(WS_WMKV), kb, 64 * nb, 64 * nb, scr, lane); }
.LBB0_18:
	s_ashr_i32 s28, s3, 6
	s_lshl_b32 s3, s10, 3
	s_lshl_b32 s38, s40, 3
	v_and_b32_e32 v20, 63, v17
	s_add_i32 s14, s3, s28
	s_cmpk_gt_i32 s14, 0x47f
	v_lshlrev_b32_e32 v178, 3, v20
	v_lshlrev_b32_e32 v176, 4, v20
	s_load_dwordx2 s[12:13], s[0:1], 0
	s_load_dwordx2 s[16:17], s[0:1], 8
	s_load_dwordx2 s[4:5], s[0:1], 16
	s_load_dwordx2 s[8:9], s[0:1], 24
	s_load_dwordx2 s[6:7], s[0:1], 32
	s_load_dwordx2 s[20:21], s[0:1], 0x58
	s_load_dwordx2 s[22:23], s[0:1], 0xa0
	s_load_dwordx2 s[18:19], s[0:1], 0xa0
	s_load_dwordx2 s[26:27], s[0:1], 0xa0
	s_waitcnt lgkmcnt(0)
	s_cbranch_scc1 .LBB0_31
	s_mul_i32 s3, s28, 0x4100
	v_lshrrev_b32_e32 v15, 3, v20
	v_and_b32_e32 v6, 56, v178
	s_add_i32 s15, s3, 0
	v_mul_u32_u24_e32 v0, 0x104, v6
	v_lshlrev_b32_e32 v2, 2, v15
	v_mov_b32_e32 v1, 0
	v_add3_u32 v16, s15, v0, v2
	v_and_b32_e32 v0, 0xf0, v176
	v_lshrrev_b32_e32 v14, 4, v20
	s_movk_i32 s29, 0x104
	v_lshl_add_u64 v[2:3], s[8:9], 0, v[0:1]
	v_mov_b32_e32 v0, s3
	v_lshlrev_b32_e32 v4, 4, v17
	v_mad_u32_u24 v0, v14, s29, v0
	v_and_b32_e32 v4, 0xf0, v4
	s_lshl_b32 s3, s10, 4
	s_lshl_b32 s15, s28, 1
	s_lshl_b32 s10, s10, 9
	s_lshl_b32 s28, s28, 6
	s_mov_b32 s11, 0
	v_or_b32_e32 v18, 8, v15
	v_or_b32_e32 v19, 16, v15
	v_or_b32_e32 v21, 24, v15
	v_or_b32_e32 v22, 32, v15
	v_or_b32_e32 v23, 40, v15
	v_or_b32_e32 v24, 48, v15
	v_or_b32_e32 v25, 56, v15
	v_add3_u32 v26, v0, v4, 0
	v_mov_b32_e32 v5, v1
	v_or_b32_e32 v27, 0xfffffb0c, v14
	s_add_i32 s3, s3, s15
	s_lshl_b32 s15, s40, 4
	s_add_i32 s33, s10, s28
	s_lshl_b32 s39, s40, 9
	v_or_b32_e32 v28, 0xfffffb08, v14
	v_or_b32_e32 v29, 0xfffffb04, v14
	v_or_b32_e32 v30, 0xfffffb00, v14
	s_mov_b64 s[28:29], 0x900000
	s_movk_i32 s42, 0x2820
	v_lshlrev_b32_e32 v0, 1, v6
	v_add_u32_e32 v31, 0x400, v16
	s_mov_b32 s43, s14
	s_branch .LBB0_21

; #define IN(i) ((const float*)KARG(i))
; #define WSB(off) ((bf16*)((unsigned char*)KARG(20) + (off)))
; __global__ void __launch_bounds__(NWAVES * 64, 2) mk_fwd(Args args) {
;     ...
;         for (int it = gw; it < I_IN + I_MKV; it += NGW) {
;             int r = it;
;             if (r < I_IN) { const int kb = r / 40, nb = r % 40; const int sc = 64 * nb; int dr = sc;
;                 if (sc < 1024) { const int i0 = sc < 512 ? sc : sc - 512; dr = 256 * (i0 / 128) + (i0 % 128) + (sc < 512 ? 0 : 128); }
;                 transpose_item(w_in, DIN, 1024, nullptr, WSB(WS_WIN), kb, sc, dr, scr, lane); continue; } r -= I_IN;
;             { const int kb = r / 32, nb = r % 32; transpose_item(IN(13), 2048, 1024, nullptr, WSB(WS_WMKV), kb, 64 * nb, 64 * nb, scr, lane); }
.LBB0_21:
	s_cmpk_gt_i32 s43, 0x27f
	s_mov_b64 s[30:31], -1
	s_cbranch_scc0 .LBB0_25
	s_and_b32 s10, s3, 0x7fffffc0
	v_add_u32_e32 v6, s10, v27
	v_add_u32_e32 v8, s10, v28
	v_add_u32_e32 v10, s10, v29
	v_add_u32_e32 v12, s10, v30
	v_ashrrev_i32_e32 v7, 31, v6
	s_lshl_b32 s30, s33, 2
	v_ashrrev_i32_e32 v9, 31, v8
	v_ashrrev_i32_e32 v11, 31, v10
	v_ashrrev_i32_e32 v13, 31, v12
	v_lshlrev_b64 v[6:7], 13, v[6:7]
	s_and_b32 s30, s30, 0x1f00
	v_lshlrev_b64 v[8:9], 13, v[8:9]
	v_lshlrev_b64 v[10:11], 13, v[10:11]
	v_lshlrev_b64 v[12:13], 13, v[12:13]
	v_or_b32_e32 v6, s30, v6
	v_or_b32_e32 v8, s30, v8
	v_or_b32_e32 v10, s30, v10
	v_or_b32_e32 v12, s30, v12
	s_load_dwordx2 s[34:35], s[0:1], 0x68
	s_load_dwordx2 s[30:31], s[0:1], 0xa0
	s_waitcnt lgkmcnt(0)
	s_nop 0
	v_lshl_add_u64 v[32:33], s[34:35], 0, v[4:5]
	v_lshl_add_u64 v[6:7], v[32:33], 0, v[6:7]
	v_lshl_add_u64 v[8:9], v[32:33], 0, v[8:9]
	v_lshl_add_u64 v[10:11], v[32:33], 0, v[10:11]
	v_lshl_add_u64 v[12:13], v[32:33], 0, v[12:13]
	s_mov_b64 s[34:35], 0
	v_mov_b32_e32 v32, v26

; #define PG8_WAIT_V(n) asm volatile("s_waitcnt vmcnt(" #n ")" ::: "memory")
; #define PG8_BAR __builtin_amdgcn_s_barrier()
; #define WSB(off) ((bf16*)((unsigned char*)KARG(20) + (off)))
; template <class Epi, class Sched>
; __device__ __forceinline__ void gemm_phase(PG8_LAS unsigned char* lds, PG8_LAS unsigned char* xl, const Gemm g, const Sched& S, const Epi& E) {
;     ...
;     const int tid = tid_, wid = __builtin_amdgcn_readfirstlane(tid >> 6), lane = tid & 63, wr = wid >> 2, wc = wid & 3, fr = lane & 15, fq = lane >> 4;
;     const int K = g.K, nt = K / BK;
;     unsigned voffA[2], voffB[2];
; #pragma unroll
;     for (int i = 0; i < 2; ++i) { int R, C; stage_rc(tid * 16 + i * 8192, R, C); const int Rb = (R & ~31) + perm32(R & 31);
;         voffA[i] = (unsigned)(R * g.lda + C) * 2u; voffB[i] = (unsigned)(Rb * g.ldb + C) * 2u; }
;     const size_t kstep = (size_t)(BK * 2);
;     const size_t hsA = (size_t)HALF * g.lda * 2, hsB = (size_t)HALF * g.ldb * 2;
;     const unsigned ldsw = (unsigned)wid * 1024u;
;     const int aoff = lds_byte(wr * 64 + fr, fq * 8), boff = lds_byte(wc * 32 + fr, fq * 8);
;     ...
;     Unit cur, nxt; int ui = 0;
;     if (!S.next(0, cur)) return;
;     Acc acc;
; #pragma unroll
;     for (int a = 0; a < 2; ++a)
; #pragma unroll
;         for (int b = 0; b < 2; ++b)
; #pragma unroll
;             for (int m = 0; m < 4; ++m)
; #pragma unroll
;                 for (int n = 0; n < 2; ++n) acc[a][b][m][n] = (f32x4){0.f, 0.f, 0.f, 0.f};
;     bf16x8 At[4][2], B0[2][2], B1[2][2];
;     const char* cA = (const char*)g.A + cur.aoff; const char* cB = (const char*)g.Bt + cur.boff;
;     PG8_STAGE(PG8_SB(0, 0), cB, voffB); PG8_STAGE(PG8_SB(0, 1), cB + hsB, voffB); PG8_STAGE(PG8_SA(0, 0), cA, voffA); PG8_STAGE(PG8_SA(0, 1), cA + hsA, voffA);
;     if (wr == 1) PG8_BAR;
;     PG8_WAIT_V(2); PG8_BAR;
;     PG8_STAGE(PG8_SB(1, 0), cB + kstep, voffB); PG8_STAGE(PG8_SA(1, 0), cA + kstep, voffA); PG8_STAGE(PG8_SB(1, 1), cB + hsB + kstep, voffB);
;     PG8_WAIT_V(6); PG8_BAR;
; __global__ void __launch_bounds__(NWAVES * 64, 2) mk_fwd(Args args) {
;     ...
;         pg8::Gemm g{WSB(WS_XN), WSB(WS_WIN), DM, DM, DM}; pg8::Sched2D S; S.init(T, ZP, G, bx, DM, DM);
;         pg8::EpiZ E{WSB(WS_Z), ZP, attn_body::C2};
;         for (int rp = 0; rp < REP_1; ++rp) pg8::gemm_phase(lds, xl, g, S, E);
.LBB0_93:
	v_readfirstlane_b32 s39, v0
	v_mov_b32_e32 v0, v220
	s_mov_b32 s34, s39
	s_ashr_i32 s71, s40, 31
	v_mov_b32_e32 v8, v220
	s_load_dwordx2 s[6:7], s[0:1], 0xa0
	s_load_dwordx2 s[2:3], s[0:1], 0xa0
	s_load_dwordx2 s[4:5], s[0:1], 0xa0
	s_waitcnt lgkmcnt(0)
	s_cmpk_lt_i32 s34, 0x500
	s_nop 0
	v_readfirstlane_b32 s14, v8
	s_cbranch_scc0 .LBB0_113
	v_lshlrev_b32_e32 v0, 4, v8
	v_add_u32_e32 v1, 0x2000, v0
	v_ashrrev_i32_e32 v2, 31, v1
	v_lshrrev_b32_e32 v2, 22, v2
	v_add_u32_e32 v2, v1, v2
	v_ashrrev_i32_e32 v9, 10, v2
	v_mul_i32_i24_e32 v2, 0x400, v9
	v_sub_u32_e32 v1, v1, v2
	v_lshrrev_b32_e32 v2, 4, v1
	v_bitop3_b32 v1, v2, v1, 32 bitop3:0x6c
	v_ashrrev_i32_e32 v2, 31, v1
	v_lshrrev_b32_e32 v2, 26, v2
	v_add_u32_e32 v2, v1, v2
	v_lshlrev_b32_e32 v3, 3, v9
	v_ashrrev_i32_e32 v10, 6, v2
	v_and_b32_e32 v3, -16, v3
	v_add_u32_e32 v3, v10, v3
	s_add_u32 s35, s6, 0x4000000
	v_and_b32_e32 v4, 3, v10
	s_mov_b32 s6, 0x1fffe0
	v_lshrrev_b32_e32 v5, 2, v3
	v_lshlrev_b32_e32 v6, 1, v3
	v_and_b32_e32 v2, 0xc0, v2
	v_and_or_b32 v4, v3, s6, v4
	v_and_b32_e32 v5, 4, v5
	v_and_b32_e32 v6, 24, v6
	v_sub_u32_e32 v1, v1, v2
	v_mov_b32_e32 v2, 1
	v_or3_b32 v4, v4, v5, v6
	v_lshlrev_b32_e32 v5, 5, v9
	v_ashrrev_i16_sdwa v1, v2, sext(v1) dst_sel:DWORD dst_unused:UNUSED_PAD src0_sel:DWORD src1_sel:BYTE_0
	v_and_b32_e32 v5, 32, v5
	v_bfe_i32 v11, v1, 0, 16
	v_add_lshl_u32 v1, v5, v11, 1
	v_lshl_add_u32 v128, v4, 11, v1
	v_lshl_add_u32 v130, v3, 11, v1
	v_bfe_i32 v1, v8, 27, 1
	v_lshrrev_b32_e32 v1, 22, v1
	v_add_u32_e32 v1, v0, v1
	v_and_b32_e32 v1, 0xfffffc00, v1
	v_sub_u32_e32 v0, v0, v1
	v_lshrrev_b32_e32 v1, 4, v0
	v_ashrrev_i32_e32 v3, 31, v8
	v_bitop3_b32 v0, v1, v0, 32 bitop3:0x6c
	v_lshrrev_b32_e32 v3, 26, v3
	v_ashrrev_i32_e32 v1, 31, v0
	v_add_u32_e32 v3, v8, v3
	v_lshrrev_b32_e32 v1, 26, v1
	v_ashrrev_i32_e32 v13, 6, v3
	v_add_u32_e32 v1, v0, v1
	v_lshlrev_b32_e32 v3, 3, v13
	v_ashrrev_i32_e32 v12, 6, v1
	v_and_b32_e32 v3, -16, v3
	s_addc_u32 s36, s7, 0
	s_ashr_i32 s37, s34, 31
	v_add_u32_e32 v3, v12, v3
	v_and_b32_e32 v4, 3, v12
	v_and_or_b32 v4, v3, s6, v4
	s_lshr_b32 s6, s37, 29
	s_add_i32 s6, s34, s6
	s_ashr_i32 s12, s14, 6
	s_ashr_i32 s7, s6, 3
	s_and_b32 s6, s6, -8
	s_ashr_i32 s15, s14, 8
	s_lshl_b32 s42, s12, 10
	s_sub_i32 s6, s34, s6
	s_cmp_lt_i32 s6, 0
	s_movk_i32 s43, 0xa1
	s_cselect_b32 s8, s43, 0xa0
	s_mul_i32 s6, s6, s8
	s_add_i32 s6, s6, s7
	s_mul_hi_i32 s7, s6, 0x66666667
	s_lshr_b32 s8, s7, 31
	s_ashr_i32 s7, s7, 5
	s_add_i32 s7, s7, s8
	s_lshl_b32 s8, s7, 3
	s_mulk_i32 s7, 0x50
	s_sub_i32 s7, s6, s7
	s_bfe_i32 s6, s7, 0x80000
	s_bfe_u32 s6, s6, 0x3000c
	s_add_i32 s9, s7, s6
	s_bfe_i32 s6, s9, 0x80000
	s_and_b32 s9, s9, 0xf8
	s_sub_i32 s7, s7, s9
	s_sext_i32_i16 s6, s6
	s_sext_i32_i8 s7, s7
	v_lshrrev_b32_e32 v5, 2, v3
	v_lshlrev_b32_e32 v6, 1, v3
	v_and_b32_e32 v1, 0xc0, v1
	s_lshr_b32 s6, s6, 3
	s_add_i32 s10, s8, s7
	v_and_b32_e32 v5, 4, v5
	v_and_b32_e32 v6, 24, v6
	v_sub_u32_e32 v0, v0, v1
	s_bfe_i64 s[8:9], s[6:7], 0x100000
	s_ashr_i32 s11, s10, 31
	v_or3_b32 v4, v4, v5, v6
	v_lshlrev_b32_e32 v5, 5, v13
	v_ashrrev_i16_sdwa v0, v2, sext(v0) dst_sel:DWORD dst_unused:UNUSED_PAD src0_sel:DWORD src1_sel:BYTE_0
	s_lshl_b64 s[8:9], s[8:9], 19
	s_lshl_b64 s[16:17], s[10:11], 19
	v_and_b32_e32 v5, 32, v5
	v_bfe_i32 v14, v0, 0, 16
	s_add_u32 s26, s2, s8
	v_add_lshl_u32 v0, v5, v14, 1
	s_addc_u32 s27, s3, s9
	s_add_i32 s52, s42, 0
	v_lshl_add_u32 v132, v4, 11, v0
	s_add_i32 m0, s52, 0x10000
	v_lshl_add_u32 v134, v3, 11, v0
	global_load_lds_dwordx4 v132, s[26:27]
	s_add_i32 m0, s52, 0x12000
	s_add_u32 s8, s26, 0x40000
	global_load_lds_dwordx4 v128, s[26:27]
	s_addc_u32 s9, s27, 0
	s_add_i32 m0, s52, 0x14000
	v_mov_b32_e32 v137, 0
	global_load_lds_dwordx4 v132, s[8:9]
	s_add_i32 m0, s52, 0x16000
	s_add_u32 s28, s35, s16
	s_addc_u32 s29, s36, s17
	s_add_i32 s53, s52, 0x2000
	global_load_lds_dwordx4 v128, s[8:9]
	s_mov_b32 m0, s52
	s_add_u32 s8, s28, 0x40000
	global_load_lds_dwordx4 v134, s[28:29]
	s_mov_b32 m0, s53
	s_addc_u32 s9, s29, 0
	s_add_i32 s54, s52, 0x4000
	global_load_lds_dwordx4 v130, s[28:29]
	s_mov_b32 m0, s54
	s_add_i32 s55, s52, 0x6000
	global_load_lds_dwordx4 v134, s[8:9]
	s_mov_b32 m0, s55
	v_mov_b32_e32 v133, v137
	global_load_lds_dwordx4 v130, s[8:9]
	v_mov_b32_e32 v129, v137
	v_mov_b32_e32 v135, v137
	v_mov_b32_e32 v131, v137
	s_cmp_eq_u32 s15, 1
	s_mov_b32 s7, 0
	v_lshl_add_u64 v[6:7], s[26:27], 0, v[132:133]
	v_lshl_add_u64 v[2:3], s[26:27], 0, v[128:129]
	s_mov_b32 s56, 0x14000
	v_lshl_add_u64 v[0:1], s[28:29], 0, v[134:135]
	s_cselect_b64 s[8:9], -1, 0
	s_cmp_lg_u32 s15, 1
	v_lshl_add_u64 v[4:5], s[28:29], 0, v[130:131]
	s_cbranch_scc1 .LBB0_96
	s_barrier

; #define PG8_STAGE(bufoff, gbase, voff) do { _Pragma("unroll") for (int _i = 0; _i < 2; ++_i) \
;         __builtin_amdgcn_global_load_lds((const unsigned*)((const char*)(gbase) + (voff)[_i]), (PG8_LAS unsigned*)(lds + (bufoff) + ldsw + _i * 8192), 16, 0, 0); } while (0)
; #define PH(n) if (ONLY < 0 || ONLY == (n))
; #define WSB(off) ((bf16*)((unsigned char*)KARG(20) + (off)))
; template <class Epi, class Sched>
; __device__ __forceinline__ void gemm_phase(PG8_LAS unsigned char* lds, PG8_LAS unsigned char* xl, const Gemm g, const Sched& S, const Epi& E) {
;     ...
;     Unit cur, nxt; int ui = 0;
;     if (!S.next(0, cur)) return;
;     Acc acc;
; #pragma unroll
;     for (int a = 0; a < 2; ++a)
; #pragma unroll
;         for (int b = 0; b < 2; ++b)
; #pragma unroll
;             for (int m = 0; m < 4; ++m)
; #pragma unroll
;                 for (int n = 0; n < 2; ++n) acc[a][b][m][n] = (f32x4){0.f, 0.f, 0.f, 0.f};
;     bf16x8 At[4][2], B0[2][2], B1[2][2];
;     const char* cA = (const char*)g.A + cur.aoff; const char* cB = (const char*)g.Bt + cur.boff;
;     PG8_STAGE(PG8_SB(0, 0), cB, voffB); PG8_STAGE(PG8_SB(0, 1), cB + hsB, voffB); PG8_STAGE(PG8_SA(0, 0), cA, voffA); PG8_STAGE(PG8_SA(0, 1), cA + hsA, voffA);
; __global__ void __launch_bounds__(NWAVES * 64, 2) mk_fwd(Args args) {
;     ...
;     PH(11) { PHASE_VARS
;         pg8::Gemm g{WSB(WS_MEMN), WSB(WS_WMKV), DM, DM, DM}; pg8::Sched2D S; S.init(NB * ML, 2 * DM, G, bx, DM, DM);
;         pg8::EpiBf16 E{WSB(WS_KVM), 2 * DM, 0, 0, 1.f};
;         pg8::gemm_phase(lds, xl, g, S, E);
.LBB0_113:
	v_mov_b32_e32 v0, v220
	s_mov_b32 s33, s39
	v_mov_b32_e32 v8, v220
	s_load_dwordx2 s[2:3], s[0:1], 0xa0
	s_load_dwordx2 s[6:7], s[0:1], 0xa0
	s_load_dwordx2 s[4:5], s[0:1], 0xa0
	s_waitcnt lgkmcnt(0)
	s_cmpk_lt_i32 s33, 0x80
	v_readfirstlane_b32 s12, v8
	s_cbranch_scc0 .LBB0_137
	s_ashr_i32 s34, s33, 31
	s_lshr_b32 s8, s34, 29
	s_add_i32 s13, s33, s8
	s_and_b32 s8, s13, -8
	s_sub_i32 s11, s33, s8
	s_cmp_gt_i32 s11, -1
	s_cbranch_scc0 .LBB0_116
	s_lshl_b32 s10, s11, 4
	s_ashr_i32 s8, s13, 3
	s_cbranch_execz .LBB0_117
	s_branch .LBB0_118

; __device__ __forceinline__ unsigned pk2(float lo, float hi) { return pg8::cvt_pk_bf16(lo, hi); }
; #define IN(i) ((const float*)KARG(i))
; #define WSB(off) ((bf16*)((unsigned char*)KARG(20) + (off)))
; __global__ void __launch_bounds__(NWAVES * 64, 2) mk_fwd(Args args) {
;     ...
;             for (int it = (bx - half) * NWAVES + wave; it < I_OUT + I_MQ + I_MO + I_GU + I_DN; it += (G - half) * NWAVES) {
;                 int r = it;
;                 if (r < I_OUT) { const int kb = r / 16, nb = r % 16; transpose_item(IN(9), 1024, 1024, nullptr, WSB(WS_WOUT), kb, 64 * nb, 64 * nb, scr, lane); continue; } r -= I_OUT;
;                 if (r < I_MQ) {
;                     const float gk = IN(10)[r]; const f32x4* wr_ = (const f32x4*)(IN(12) + (size_t)r * DM) + lane; unsigned long long* o8 = (unsigned long long*)(WSB(WS_WMQ2) + (size_t)r * 2048) + lane;
; #pragma unroll
;                     for (int j = 0; j < 4; ++j) { const f32x4 v = wr_[64 * j] * gk; o8[64 * j] = (unsigned long long)pk2(v[0], v[1]) | ((unsigned long long)pk2(v[2], v[3]) << 32); }
;                     continue; } r -= I_MQ;
;                 if (r < I_MO) { const int kb = r / 16, nb = r % 16; transpose_item(IN(14), 1024, 2048, nullptr, WSB(WS_WMO2), kb, 64 * nb, 64 * nb, scr, lane); continue; } r -= I_MO;
;                 if (r < I_GU) { const int kb = r / 88, nb = r % 88; const int sc = 64 * nb; const int i0 = sc < DFF ? sc : sc - DFF; const int dr = 256 * (i0 / 128) + (i0 % 128) + (sc < DFF ? 0 : 128);
;                     transpose_item(IN(16), 2 * DFF, 1024, IN(15), WSB(WS_WGU), kb, sc, dr, scr, lane); continue; } r -= I_GU;
.LBB0_148:
	s_and_b64 vcc, exec, s[4:5]
	s_cbranch_vccz .LBB0_160
	s_add_i32 s2, s31, 0xfa00
	s_and_b32 s55, s2, 0xffff
	s_mul_i32 s4, s55, 0xba2f
	s_lshr_b32 s20, s4, 16
	s_lshr_b32 s4, s4, 22
	s_mulk_i32 s4, 0x58
	s_sub_i32 s54, s2, s4
	s_lshl_b32 s53, s54, 6
	s_and_b32 s52, s20, 0xffc0
	s_load_dwordx2 s[4:5], s[0:1], 0x80
	s_load_dwordx2 s[18:19], s[0:1], 0x78
	s_waitcnt lgkmcnt(0)
	s_cmp_lg_u64 s[18:19], 0
	s_cselect_b64 s[22:23], -1, 0
	s_lshl_b32 s2, s54, 8
	v_or_b32_e32 v2, s52, v42
	s_and_b32 s2, s2, 0x3ff00
	v_mul_u32_u24_e32 v6, 0x5800, v2
	v_lshl_add_u64 v[0:1], s[4:5], 0, v[10:11]
	v_lshl_add_u64 v[2:3], s[2:3], 0, v[6:7]
	v_lshl_add_u64 v[16:17], v[0:1], 0, v[2:3]
	v_or_b32_e32 v2, s52, v43
	v_mul_u32_u24_e32 v6, 0x5800, v2
	v_lshl_add_u64 v[2:3], s[2:3], 0, v[6:7]
	v_lshl_add_u64 v[20:21], v[0:1], 0, v[2:3]
	v_or_b32_e32 v2, s52, v44
	v_mul_u32_u24_e32 v6, 0x5800, v2
	v_lshl_add_u64 v[2:3], s[2:3], 0, v[6:7]
	s_mul_hi_u32 s4, s55, 0x2e8ba2f
	v_lshl_add_u64 v[22:23], v[0:1], 0, v[2:3]
	v_or_b32_e32 v6, s52, v13
	v_mov_b64_e32 v[2:3], s[2:3]
	v_lshl_or_b32 v18, s4, 8, v12
	v_mad_u64_u32 v[2:3], s[4:5], v6, s42, v[2:3]
	s_mov_b64 s[20:21], 0
	v_mov_b32_e32 v19, v5
	v_lshl_add_u64 v[24:25], v[0:1], 0, v[2:3]
	v_lshlrev_b32_e32 v6, 2, v6
	v_mov_b32_e32 v15, v37
	s_load_dwordx2 s[16:17], s[0:1], 0xa0
	s_waitcnt lgkmcnt(0)

; #define PH(n) if (ONLY < 0 || ONLY == (n))
; #define IN(i) ((const float*)KARG(i))
; #define WSB(off) ((bf16*)((unsigned char*)KARG(20) + (off)))
; #define WSF(off) ((float*)((unsigned char*)KARG(20) + (off)))
; __global__ void __launch_bounds__(NWAVES * 64, 2) mk_fwd(Args args) {
;     ...
;     PH(2) { PHASE_VARS
;         const float* LOGF = WSF(WS_LOGF); bf16* Z = WSB(WS_Z); bf16* CAT = WSB(WS_CAT);
;         const float* conv_w = IN(5); const float* conv_b = IN(6); const float* ln_g = IN(7); const float* ln_b = IN(8);
;         const int NV = G;
;         for (int repa = 0; repa < REPA; ++repa)
;         for (int v0 = vcu; v0 < 256; v0 += NV) {
;             const int bh = v0 >> 1, b = bh >> 3, h = bh & 7, sel = v0 & 1;
.LBB0_235:
	s_load_dwordx2 s[2:3], s[0:1], 0xa0
	s_waitcnt lgkmcnt(0)
	s_cmpk_gt_i32 s73, 0xff
	s_load_dwordx2 s[2:3], s[0:1], 0xa0
	s_load_dwordx2 s[10:11], s[0:1], 0xa0
	s_load_dwordx2 s[18:19], s[0:1], 40
	s_load_dwordx2 s[16:17], s[0:1], 48
	s_load_dwordx2 s[12:13], s[0:1], 56
	s_load_dwordx2 s[14:15], s[0:1], 64
	s_waitcnt lgkmcnt(0)
	s_cbranch_scc1 .LBB0_352
	s_add_u32 s74, s2, 0x8000800
	s_addc_u32 s75, s3, 0
	s_add_u32 s76, s2, 0x8000c00
	s_addc_u32 s77, s3, 0
	s_add_u32 s78, s2, 0x8001000
	s_addc_u32 s79, s3, 0
	s_add_u32 s80, s10, 0x14000400
	s_addc_u32 s81, s11, 0
	s_add_i32 s82, 0, 0x14800
	v_lshl_add_u32 v221, v200, 4, s82
	s_mov_b32 s21, 0
	v_cmp_eq_u32_e64 s[4:5], 0, v200
	v_ashrrev_i32_e32 v201, 31, v200
	v_add_u32_e32 v222, 0x2000, v221
	v_add_u32_e32 v223, 0x4000, v221
	v_add_u32_e32 v224, 0x6000, v221
	v_mov_b32_e32 v99, 0
	s_add_i32 s83, 0, 0x1c800
	s_mov_b64 s[22:23], 0x50000
	s_mov_b64 s[26:27], 0xa0000
	s_mov_b64 s[28:29], 0x8140c00
	s_mov_b64 s[30:31], 0x80a1000
	s_mov_b32 s84, 0x42c00000
	v_mov_b32_e32 v225, 0x3f80
	v_mov_b32_e32 v226, 0x3f803f80
	v_mov_b32_e32 v227, 0x200
	v_mov_b32_e32 v228, 0xff800000
	v_mov_b32_e32 v229, 0x400
	s_mov_b32 s85, s73
	s_branch .LBB0_238

; #define PH(n) if (ONLY < 0 || ONLY == (n))
; #define WSB(off) ((bf16*)((unsigned char*)KARG(20) + (off)))
; __global__ void __launch_bounds__(NWAVES * 64, 2) mk_fwd(Args args) {
;     ...
;     PH(14) { PHASE_VARS
;         const bf16* wsb = WSB(0);
;         pg8::Gemm g{wsb, wsb, 2048, 2048, 256}; pg8::SchedKV S; S.init(G, bx, WS_KVM, WS_WMQ2, WS_WMO2);
;         pg8::EpiBf16x2 E{WSB(WS_WK), WSB(WS_VW), DM, LOG2E / 16.f};
;         pg8::gemm_phase(lds, xl, g, S, E);
.LBB0_361:
	v_mov_b32_e32 v0, v220
	s_mov_b32 s42, s39
	v_mov_b32_e32 v8, v220
	s_load_dwordx2 s[2:3], s[0:1], 0xa0
	s_load_dwordx2 s[4:5], s[0:1], 0xa0
	s_load_dwordx2 s[10:11], s[0:1], 0xa0
	s_waitcnt lgkmcnt(0)
	s_cmpk_lt_i32 s42, 0x200
	v_readfirstlane_b32 s12, v8
	s_cbranch_scc0 .LBB0_385
	s_lshl_b32 s6, s42, 5
	s_lshr_b32 s7, s42, 3
	s_and_b32 s6, s6, 0xe0
	s_and_b32 s7, s7, 16
	s_or_b32 s13, s6, s7
	s_bfe_u32 s14, s42, 0x20003
	s_bfe_u32 s16, s42, 0x20005
	s_cmpk_gt_u32 s42, 0xff
	s_cbranch_scc0 .LBB0_364
	s_lshl_b32 s6, s14, 20
	s_lshl_b32 s7, s16, 9
	s_or_b32 s6, s6, s7
	s_or_b32 s8, s6, 0x1c400000
	s_lshl_b32 s6, s13, 16
	s_or_b32 s6, s6, s7
	s_lshl_b32 s15, s14, 8
	s_or_b32 s9, s6, 0x800
	s_lshl_b32 s26, s16, 8
	s_mov_b64 s[6:7], 0x2e00000
	s_cbranch_execz .LBB0_365
	s_branch .LBB0_366

; #define PH(n) if (ONLY < 0 || ONLY == (n))
; #define IN(i) ((const float*)KARG(i))
; #define WSB(off) ((bf16*)((unsigned char*)KARG(20) + (off)))
; #define WSF(off) ((float*)((unsigned char*)KARG(20) + (off)))
; __global__ void __launch_bounds__(NWAVES * 64, 2) mk_fwd(Args args) {
;     ...
;     PH(3) { PHASE_VARS
;         pg8::Gemm g{WSB(WS_CAT), WSB(WS_WOUT), DM, DM, DM}; pg8::Sched2D S; S.init(T, DM, G, bx, DM, DM);
;         pg8::EpiRes<false> E{IN(0), WSB(WS_XN), WSF(WS_SS1)};
;         pg8::gemm_phase(lds, xl, g, S, E);
.LBB0_449:
	s_or_b64 exec, exec, s[2:3]
	v_mov_b32_e32 v0, v220
	s_mov_b32 s42, s39
	s_waitcnt lgkmcnt(0)
	v_mov_b32_e32 v8, v220
	s_cmpk_lt_i32 s42, 0x200
	s_load_dwordx2 s[12:13], s[0:1], 0xa0
	s_load_dwordx2 s[14:15], s[0:1], 0xa0
	s_load_dwordx2 s[2:3], s[0:1], 0
	s_load_dwordx2 s[8:9], s[0:1], 0xa0
	s_load_dwordx2 s[6:7], s[0:1], 0xa0
	s_waitcnt lgkmcnt(0)
	s_cselect_b64 s[18:19], -1, 0
	s_cmpk_gt_i32 s42, 0x1ff
	v_readfirstlane_b32 s20, v8
	s_cbranch_scc1 .LBB0_452
	s_ashr_i32 s4, s42, 31
	s_lshr_b32 s4, s4, 29
	s_add_i32 s16, s42, s4
	s_and_b32 s4, s16, -8
	s_sub_i32 s10, s42, s4
	s_cmp_gt_i32 s10, -1
	s_cbranch_scc0 .LBB0_453
	s_lshl_b32 s11, s10, 6
	s_ashr_i32 s4, s16, 3
	s_cbranch_execz .LBB0_454
	s_branch .LBB0_455

; #define PH(n) if (ONLY < 0 || ONLY == (n))
; #define WSB(off) ((bf16*)((unsigned char*)KARG(20) + (off)))
; #define WSF(off) ((float*)((unsigned char*)KARG(20) + (off)))
; __global__ void __launch_bounds__(NWAVES * 64, 2) mk_fwd(Args args) {
;     ...
;     PH(4) { PHASE_VARS
;         pg8::Gemm g{WSB(WS_XN), WSB(WS_WK), DM, DM, DM}; pg8::Sched2D S; S.init(T, DM, G, bx, DM, DM, (size_t)DM * DM * 2);
;         pg8::EpiSoftmax E{WSB(WS_P), DM, WSF(WS_SS1)};
;         pg8::gemm_phase(lds, xl, g, S, E);
.LBB0_558:
	s_or_b64 exec, exec, s[2:3]
	v_mov_b32_e32 v0, v220
	s_mov_b32 s42, s39
	s_waitcnt lgkmcnt(0)
	v_mov_b32_e32 v8, v220
	s_cmpk_lt_i32 s42, 0x200
	s_load_dwordx2 s[2:3], s[0:1], 0xa0
	s_load_dwordx2 s[14:15], s[0:1], 0xa0
	s_load_dwordx2 s[8:9], s[0:1], 0xa0
	s_load_dwordx2 s[6:7], s[0:1], 0xa0
	s_waitcnt lgkmcnt(0)
	s_cselect_b64 s[18:19], -1, 0
	s_cmpk_gt_i32 s42, 0x1ff
	v_readfirstlane_b32 s13, v8
	s_cbranch_scc1 .LBB0_561
	s_ashr_i32 s10, s42, 31
	s_lshr_b32 s10, s10, 29
	s_add_i32 s17, s42, s10
	s_and_b32 s10, s17, -8
	s_sub_i32 s12, s42, s10
	s_cmp_gt_i32 s12, -1
	s_cbranch_scc0 .LBB0_562
	s_lshl_b32 s16, s12, 6
	s_ashr_i32 s10, s17, 3
	s_cbranch_execz .LBB0_563
	s_branch .LBB0_564

; #define PH(n) if (ONLY < 0 || ONLY == (n))
; #define WSB(off) ((bf16*)((unsigned char*)KARG(20) + (off)))
; #define WSF(off) ((float*)((unsigned char*)KARG(20) + (off)))
; __global__ void __launch_bounds__(NWAVES * 64, 2) mk_fwd(Args args) {
;     ...
;     PH(7) { PHASE_VARS
;         pg8::Gemm g{WSB(WS_P), WSB(WS_VW), DM, DM, DM}; pg8::Sched2D S; S.init(T, DM, G, bx, DM, DM, (size_t)DM * DM * 2);
;         pg8::EpiRes<true> E{WSB(WS_XN), WSB(WS_XN), WSF(WS_SS2)};
;         pg8::gemm_phase(lds, xl, g, S, E);
.LBB0_706:
	s_or_b64 exec, exec, s[2:3]
	v_mov_b32_e32 v0, v220
	s_mov_b32 s42, s39
	s_waitcnt lgkmcnt(0)
	v_mov_b32_e32 v8, v220
	s_cmpk_lt_i32 s42, 0x200
	s_load_dwordx2 s[12:13], s[0:1], 0xa0
	s_load_dwordx2 s[14:15], s[0:1], 0xa0
	s_load_dwordx2 s[10:11], s[0:1], 0xa0
	s_load_dwordx2 s[8:9], s[0:1], 0xa0
	s_load_dwordx2 s[6:7], s[0:1], 0xa0
	s_waitcnt lgkmcnt(0)
	s_cselect_b64 s[18:19], -1, 0
	s_cmpk_gt_i32 s42, 0x1ff
	v_readfirstlane_b32 s20, v8
	s_cbranch_scc1 .LBB0_709
	s_ashr_i32 s2, s42, 31
	s_lshr_b32 s2, s2, 29
	s_add_i32 s21, s42, s2
	s_and_b32 s2, s21, -8
	s_sub_i32 s16, s42, s2
	s_cmp_gt_i32 s16, -1
	s_cbranch_scc0 .LBB0_710
	s_lshl_b32 s17, s16, 6
	s_ashr_i32 s2, s21, 3
	s_cbranch_execz .LBB0_711
	s_branch .LBB0_712

; #define PH(n) if (ONLY < 0 || ONLY == (n))
; #define WSB(off) ((bf16*)((unsigned char*)KARG(20) + (off)))
; #define WSF(off) ((float*)((unsigned char*)KARG(20) + (off)))
; __global__ void __launch_bounds__(NWAVES * 64, 2) mk_fwd(Args args) {
;     ...
;     PH(8) { PHASE_VARS
;         pg8::Gemm g{WSB(WS_XN), WSB(WS_WGU), DM, DM, DM}; pg8::Sched2D S; S.init(T, 2 * DFF, G, bx, DM, DM);
;         pg8::EpiSwiGLU E{WSB(WS_HMID), DFF, WSF(WS_SS2)};
;         pg8::gemm_phase(lds, xl, g, S, E);
.LBB0_814:
	s_or_b64 exec, exec, s[2:3]
	s_mov_b32 s99, -1
	v_mov_b32_e32 v0, v220
	s_mov_b32 s36, s39
	v_mov_b32_e32 v10, v220
	s_waitcnt lgkmcnt(0)
	s_load_dwordx2 s[2:3], s[0:1], 0xa0
	s_load_dwordx2 s[8:9], s[0:1], 0xa0
	s_load_dwordx2 s[12:13], s[0:1], 0xa0
	s_load_dwordx2 s[6:7], s[0:1], 0xa0
	s_waitcnt lgkmcnt(0)
	s_cmpk_gt_i32 s36, 0xaff
	v_readfirstlane_b32 s18, v10
	s_cbranch_scc0 .LBB0_817
	s_and_saveexec_b64 s[2:3], s[48:49]
	s_xor_b64 s[48:49], exec, s[2:3]
	s_cbranch_execnz .LBB0_834

; #define PH(n) if (ONLY < 0 || ONLY == (n))
; #define IN(i) ((const float*)KARG(i))
; #define WSB(off) ((bf16*)((unsigned char*)KARG(20) + (off)))
; #define WSF(off) ((float*)((unsigned char*)KARG(20) + (off)))
; __global__ void __launch_bounds__(NWAVES * 64, 2) mk_fwd(Args args) {
;     ...
;     PH(9) { PHASE_VARS
;         pg8::Gemm g{WSB(WS_HMID), WSB(WS_WDN), DFF, DFF, DFF}; pg8::Sched2D S; S.init(T, DM, G, bx, DFF, DFF);
;         if (G == 256) {
;             pg8::EpiFinal E{WSB(WS_XN), OUTP, IN(18), WSF(WS_SS3), (unsigned*)WSF(WS_CNT)};
;             pg8::gemm_phase(lds, xl, g, S, E);
;         } else {
;             pg8::EpiResF32 E{WSB(WS_XN), OUTP};
;             pg8::gemm_phase(lds, xl, g, S, E);
.LBB0_896:
	s_or_b64 exec, exec, s[2:3]
	v_mov_b32_e32 v0, v220
	s_mov_b32 s54, s39
	s_waitcnt lgkmcnt(0)
	s_load_dwordx2 s[2:3], s[0:1], 0xa0
	s_waitcnt lgkmcnt(0)
	s_add_u32 s55, s2, 0x8000000
	s_addc_u32 s56, s3, 0
	v_readlane_b32 s6, v255, 2
	s_load_dwordx2 s[2:3], s[0:1], 0xa0
	s_waitcnt lgkmcnt(0)
	s_add_u32 s57, s2, 0x1a00000
	v_readlane_b32 s7, v255, 3
	s_addc_u32 s58, s3, 0
	s_mov_b64 s[2:3], -1
	s_and_b64 vcc, exec, s[6:7]
	s_cbranch_vccz .LBB0_922
	v_mov_b32_e32 v8, v220
	s_load_dwordx2 s[6:7], s[0:1], 0xa0
	s_load_dwordx2 s[2:3], s[0:1], 0x98
	s_waitcnt lgkmcnt(0)
	s_cmpk_gt_i32 s54, 0x1ff
	v_readfirstlane_b32 s14, v8
	s_cbranch_scc1 .LBB0_921
	s_ashr_i32 s36, s54, 31
	s_lshr_b32 s8, s36, 29
	s_add_i32 s12, s54, s8
	s_and_b32 s8, s12, -8
	s_sub_i32 s11, s54, s8
	s_cmp_gt_i32 s11, -1
	s_cbranch_scc0 .LBB0_900
	s_lshl_b32 s10, s11, 6
	s_ashr_i32 s8, s12, 3
	s_cbranch_execz .LBB0_901
	s_branch .LBB0_902

; #define PH(n) if (ONLY < 0 || ONLY == (n))
; #define IN(i) ((const float*)KARG(i))
; #define WSB(off) ((bf16*)((unsigned char*)KARG(20) + (off)))
; #define WSF(off) ((float*)((unsigned char*)KARG(20) + (off)))
; __global__ void __launch_bounds__(NWAVES * 64, 2) mk_fwd(Args args) {
;     ...
;     PH(9) { PHASE_VARS
;         pg8::Gemm g{WSB(WS_HMID), WSB(WS_WDN), DFF, DFF, DFF}; pg8::Sched2D S; S.init(T, DM, G, bx, DFF, DFF);
;         if (G == 256) {
;             pg8::EpiFinal E{WSB(WS_XN), OUTP, IN(18), WSF(WS_SS3), (unsigned*)WSF(WS_CNT)};
;             pg8::gemm_phase(lds, xl, g, S, E);
.LBB0_922:
	s_andn2_b64 vcc, exec, s[2:3]
	s_cbranch_vccnz .LBB0_981
	v_mov_b32_e32 v8, v220
	s_cmpk_lt_i32 s54, 0x200
	s_load_dwordx2 s[6:7], s[0:1], 0xa0
	s_load_dwordx2 s[12:13], s[0:1], 0x98
	s_load_dwordx2 s[14:15], s[0:1], 0x90
	s_load_dwordx2 s[10:11], s[0:1], 0xa0
	s_load_dwordx2 s[8:9], s[0:1], 0xa0
	s_waitcnt lgkmcnt(0)
	s_cselect_b64 s[18:19], -1, 0
	s_cmpk_gt_i32 s54, 0x1ff
	v_readfirstlane_b32 s26, v8
	s_cbranch_scc1 .LBB0_926
	s_ashr_i32 s2, s54, 31
	s_lshr_b32 s2, s2, 29
	s_add_i32 s16, s54, s2
	s_and_b32 s2, s16, -8
	s_sub_i32 s17, s54, s2
	s_cmp_gt_i32 s17, -1
	s_cbranch_scc0 .LBB0_927
	s_lshl_b32 s20, s17, 6
	s_cbranch_execz .LBB0_928
	s_branch .LBB0_929
